# bundle11 + P7 phase entry staggered by XCD index (s_sleep 64 per step) to spread the gate-load bursts of the in-loop rescales
# speedup vs baseline: 1.0020x; 1.0003x over previous
.LBB0_1307:
	s_cmp_lt_i32 s24, 8
	s_cselect_b64 s[0:1], -1, 0
	s_cmp_gt_i32 s25, 7
	s_cselect_b64 s[2:3], -1, 0
	s_and_b64 s[0:1], s[0:1], s[2:3]
	s_andn2_b64 vcc, exec, s[0:1]
	s_cbranch_vccnz .LBB0_1390
	s_and_b32 s32, s20, 7
	s_cmp_eq_u32 s32, 0
	s_cbranch_scc1 .Lstg_p7_done
.Lstg_p7_loop:
	s_sleep 64
	s_sub_u32 s32, s32, 1
	s_cmp_lg_u32 s32, 0
	s_cbranch_scc1 .Lstg_p7_loop
